# v12: EpiNorm epilogues rewritten (x in accumulators, 16B merged bf16 stores via permlane16 swap) + XCD-aware unit order for the K=256 GEMM stream
# speedup vs baseline: 1.0158x; 1.0158x over previous
; __device__ __forceinline__ void p3_pool(Frame& F) {
;     ...
;     const int gw = F.vcu * NWAVES + F.wave, NGW = F.G * NWAVES;
;     const bool remap = F.G == 256;
;     for (int it = 0;; ++it) {
;         int tk2 = gw + it * NGW;
;         if (remap) { if (it == 1) { if ((int)blockIdx.x < 192 || F.wave >= 4) break; tk2 = 2048 + ((int)blockIdx.x - 192) * 4 + F.wave; } else if (it > 1) break; }
;         if (tk2 >= 2 * (NPR / 32 + DBATCH)) break;
;         const int tk = tk2 >> 1, c0 = (tk2 & 1) * 256 + lane * 4, w = 2 << (c0 >> 7);
;         const bool isP = tk < NPR / 32;
;         const int b = isP ? (tk >> 6) : (tk - NPR / 32), s0 = isP ? ((tk & 63) << 5) : 0, nsteps = isP ? 47 : 23;
.LBB0_514:
	s_or_b64 exec, exec, s[6:7]
	s_mov_b64 s[6:7], s[0:1]
	s_waitcnt lgkmcnt(0)
	s_barrier
	v_mbcnt_lo_u32_b32 v2, -1, 0
	v_mbcnt_hi_u32_b32 v2, -1, v2
	s_load_dwordx2 s[6:7], s[6:7], 0xc8
	s_mov_b64 s[8:9], s[0:1]
	s_load_dwordx2 s[8:9], s[8:9], 0xc0
	s_mov_b64 s[10:11], s[0:1]
	s_waitcnt lgkmcnt(0)
	s_add_u32 s12, s6, 0x6400000
	s_addc_u32 s13, s7, 0
	s_cmpk_gt_i32 s81, 0xbf
	s_load_dwordx2 s[14:15], s[10:11], 0x20
	s_cselect_b64 s[10:11], -1, 0
	s_lshl_b32 s3, s81, 2
	s_add_i32 s3, s3, s78
	v_lshlrev_b32_e32 v32, 2, v2
	v_lshlrev_b32_e32 v2, 3, v2
	v_and_b32_e32 v4, 0x1f8, v2
	v_mov_b32_e32 v2, 0
	s_add_u32 s16, s8, 0xa998000
	v_mov_b32_e32 v5, v2
	s_addc_u32 s17, s9, 0
	v_lshl_add_u64 v[4:5], s[6:7], 0, v[4:5]
	s_mov_b64 s[6:7], 0x11800000
	s_cmpk_lt_u32 s76, 0x100
	v_lshl_add_u64 v[12:13], v[4:5], 0, s[6:7]
	s_cselect_b64 s[6:7], -1, 0
	v_cndmask_b32_e64 v3, 0, 1, s[4:5]
	s_and_b64 s[18:19], s[10:11], s[6:7]
	s_addk_i32 s3, 0x500
	s_mov_b32 s21, 0
	v_cmp_ne_u32_e64 s[72:73], 1, v3
	s_mov_b32 s4, 0x1080000
	v_mov_b32_e32 v33, 0x7800
	s_mov_b32 s5, 0
	s_branch .LBB0_517

.LBB0_799:
	s_mov_b64 s[4:5], s[0:1]
	s_load_dwordx2 s[18:19], s[4:5], 0xc8
	s_mov_b64 s[4:5], s[0:1]
	s_load_dwordx2 s[6:7], s[4:5], 0xc8
	s_mov_b64 s[4:5], s[0:1]
	s_load_dwordx2 s[8:9], s[4:5], 0xc8
	s_mov_b64 s[4:5], s[0:1]
	s_load_dwordx2 s[10:11], s[4:5], 0xc8
	s_mov_b64 s[4:5], s[0:1]
	s_load_dwordx2 s[12:13], s[4:5], 0xc8
	s_mov_b64 s[4:5], s[0:1]
	s_load_dwordx2 s[20:21], s[4:5], 0x90
	s_mov_b64 s[4:5], s[0:1]
	s_waitcnt lgkmcnt(0)
	s_load_dwordx2 s[14:15], s[4:5], 0xc8
	s_cmpk_gt_i32 s81, 0x1ff
	s_cselect_b64 s[46:47], -1, 0
	s_cmpk_lt_i32 s81, 0x200
	s_mov_b32 s35, 0
	v_mbcnt_lo_u32_b32 v10, -1, 0
	v_mbcnt_hi_u32_b32 v10, -1, v10
	s_cbranch_scc1 .LBB0_809
	s_cmpk_lt_u32 s81, 0x494
	s_cselect_b32 s3, 2, 3
	s_cmpk_gt_u32 s81, 0x38b
	s_cselect_b32 s3, s3, 1
	s_cmp_lt_i32 s3, 2
	s_cbranch_scc1 .LBB0_803
	s_cmp_lg_u32 s3, 2
	s_cbranch_scc0 .LBB0_804
	s_add_i32 s67, s81, 0xfffffb6c
	s_branch .LBB0_805

;     __device__ __forceinline__ const char* a_ptr(const Gemm& g, const Unit& u, size_t tsA) const { return (const char*)g.A + (size_t)u.pm * tsA + (size_t)u.pn * g.a_pn_bytes + (u.ks > 0 ? (size_t)u.ks * g.ks_bytes : 0); }
;     __device__ __forceinline__ const char* b_ptr(const Gemm& g, const Unit& u, size_t tsB) const { return (const char*)g.Bt + (size_t)u.pn * tsB + (u.ks > 0 ? (size_t)u.ks * g.ks_bytes : 0); }
;     __device__ __forceinline__ const char* a_ptr(const Gemm& g, const Unit& u, size_t tsA) const { return (const char*)g.A + (size_t)u.pm * tsA + (size_t)u.pn * g.a_pn_bytes + (u.ks > 0 ? (size_t)u.ks * g.ks_bytes : 0); }
;     __device__ __forceinline__ const char* b_ptr(const Gemm& g, const Unit& u, size_t tsB) const { return (const char*)g.Bt + (size_t)u.pn * tsB + (u.ks > 0 ? (size_t)u.ks * g.ks_bytes : 0); }
;     __device__ __forceinline__ const char* a_ptr(const Gemm&, const Unit& u, size_t tsA) const {
;         const bf16_t* base = u.g == 0 ? A0 : u.g == 1 ? A1 : u.g == 2 ? A2 : A3; return (const char*)base + (size_t)u.pm * tsA + (u.g == 2 ? (size_t)u.pn * a2_pn_bytes : 0); }
;     __device__ __forceinline__ const char* b_ptr(const Gemm&, const Unit& u, size_t tsB) const {
;         const bf16_t* base = u.g == 0 ? B0 : u.g == 1 ? B1 : u.g == 2 ? B2 : B3; return (const char*)base + (size_t)u.pn * tsB; }
.LBB0_805:
	s_mov_b64 s[48:49], 0
	s_mov_b32 s35, 3
	s_andn2_b64 vcc, exec, s[58:59]
	s_mov_b64 s[58:59], 0
	s_cbranch_vccnz .LBB0_807
	s_add_i32 s67, s81, 0xfffffc74
	s_mov_b64 s[58:59], -1
	s_mov_b32 s35, 2
.LBB0_807:
	s_andn2_b64 vcc, exec, s[48:49]
	s_cbranch_vccnz .LBB0_809
	s_add_i32 s67, s81, 0xfffffe00
	s_mov_b64 s[58:59], 0
	s_mov_b32 s35, 1
.LBB0_809:
	s_lshl_b32 s31, s78, 5
	s_and_b32 s3, s31, 0x60
	v_writelane_b32 v237, s3, 18
	s_lshr_b32 s3, s3, 3
	s_add_i32 s24, s81, 0xfffffe00
	s_and_b64 s[4:5], s[58:59], exec
	v_writelane_b32 v237, s3, 22
	s_cselect_b32 s3, 2, 8
	s_cmpk_gt_u32 s24, 0x18b
	s_cselect_b32 s3, s3, 3
	s_and_b64 s[4:5], s[46:47], exec
	s_cselect_b32 s3, s3, 4
	v_cvt_f32_ubyte0_e32 v2, s3
	v_rcp_iflag_f32_e32 v2, v2
	s_add_i32 s24, s2, 0xfffffe00
	v_writelane_b32 v237, s24, 23
	s_cmpk_gt_i32 s81, 0x4b3
	v_writelane_b32 v237, s72, 24
	v_mul_f32_e32 v2, 0x4f7ffffe, v2
	v_cvt_u32_f32_e32 v2, v2
	v_writelane_b32 v237, s73, 25
	v_readfirstlane_b32 s5, v2
	s_cbranch_scc1 .LBB0_963
	s_sub_i32 s24, 0, s3
	s_mul_i32 s24, s24, s5
	s_mul_hi_u32 s24, s5, s24
	s_abs_i32 s4, s67
	s_add_i32 s5, s5, s24
	s_add_u32 s38, s38, 0x10200000
	s_addc_u32 s39, s39, 0
	s_add_u32 s24, s40, 0xf000000
	s_addc_u32 s25, s41, 0
	v_writelane_b32 v237, s24, 26
	s_mul_hi_u32 s5, s4, s5
	s_nop 0
	v_writelane_b32 v237, s25, 27
	s_add_u32 s24, s42, 0x11800000
	s_addc_u32 s25, s43, 0
	s_add_u32 s44, s44, 0x10000000
	s_addc_u32 s45, s45, 0
	v_writelane_b32 v237, s24, 28
	s_cmp_lt_i32 s35, 2
	s_nop 0
	v_writelane_b32 v237, s25, 29
	s_cbranch_scc1 .LBB0_816
	s_cmp_gt_i32 s35, 2
	s_mov_b64 s[46:47], -1
	s_cbranch_scc0 .LBB0_813
	s_mov_b64 s[46:47], 0

;     __device__ __forceinline__ const char* a_ptr(const Gemm& g, const Unit& u, size_t tsA) const { return (const char*)g.A + (size_t)u.pm * tsA + (size_t)u.pn * g.a_pn_bytes + (u.ks > 0 ? (size_t)u.ks * g.ks_bytes : 0); }
;     __device__ __forceinline__ const char* b_ptr(const Gemm& g, const Unit& u, size_t tsB) const { return (const char*)g.Bt + (size_t)u.pn * tsB + (u.ks > 0 ? (size_t)u.ks * g.ks_bytes : 0); }
;     __device__ __forceinline__ const char* a_ptr(const Gemm& g, const Unit& u, size_t tsA) const { return (const char*)g.A + (size_t)u.pm * tsA + (size_t)u.pn * g.a_pn_bytes + (u.ks > 0 ? (size_t)u.ks * g.ks_bytes : 0); }
;     __device__ __forceinline__ const char* b_ptr(const Gemm& g, const Unit& u, size_t tsB) const { return (const char*)g.Bt + (size_t)u.pn * tsB + (u.ks > 0 ? (size_t)u.ks * g.ks_bytes : 0); }
; #define PG8_STAGE(bufoff, gbase, voff) do { _Pragma("unroll") for (int _i = 0; _i < 2; ++_i) \
;         __builtin_amdgcn_global_load_lds((const unsigned*)((const char*)(gbase) + (voff)[_i]), (PG8_LAS unsigned*)(lds + (bufoff) + ldsw + _i * 8192), 16, 0, 0); } while (0)
; #define PG8_WAIT_V(n) asm volatile("s_waitcnt vmcnt(" #n ")" ::: "memory")
; template <class Epi, class Sched, bool ALIGN_EPI = false, bool SP2 = false>
; __device__ __forceinline__ void gemm_phase(PG8_LAS unsigned char* lds, const Gemm g, const Sched& S, const Epi& E, const int wid) {
;     ...
;     Unit cur, nxt; int ui = 0;
;     if (!S.next(0, cur)) return;
;     f32x4 acc[2][2][4][2];
; #pragma unroll
;     for (int a = 0; a < 2; ++a)
; #pragma unroll
;         for (int b = 0; b < 2; ++b)
; #pragma unroll
;             for (int m = 0; m < 4; ++m)
; #pragma unroll
;                 for (int n = 0; n < 2; ++n) acc[a][b][m][n] = (f32x4){0.f, 0.f, 0.f, 0.f};
;     bf16x8 At[4][2], B0[2][2], B1[2][2];
;     const char* cA = S.a_ptr(g, cur, tsA); const char* cB = S.b_ptr(g, cur, tsB);
;     S.a_ready(cur);
;     if constexpr (SP2) {
;         PG8_STAGE(PG8_SB(0, 0), cB, voffB); PG8_STAGE(PG8_SB(0, 1), cB + hsB, voffB); PG8_STAGE(PG8_SA(0, 0), cA, voffA); PG8_STAGE(PG8_SA(0, 1), cA + hsA, voffA);
;         if (wr == 1) PG8_BAR;
;         PG8_WAIT_V(2); PG8_BAR;
;         PG8_STAGE(PG8_SB(1, 0), cB + kstep, voffB); PG8_STAGE(PG8_SA(1, 0), cA + kstep, voffA); PG8_STAGE(PG8_SB(1, 1), cB + hsB + kstep, voffB);
;         PG8_WAIT_V(6); PG8_BAR;
.LBB0_849:
	s_add_u32 s64, s6, 0x16c00000
	s_addc_u32 s65, s7, 0
	s_add_u32 s66, s8, 0x13a00000
	s_addc_u32 s67, s9, 0
	s_add_u32 s68, s10, 0x1e00000
	s_addc_u32 s69, s11, 0
	s_add_u32 s70, s12, 0x1b000000
	v_and_b32_e32 v11, 15, v10
	s_addc_u32 s71, s13, 0
	v_or_b32_e32 v12, s29, v11
	s_waitcnt lgkmcnt(0)
	s_add_u32 s72, s14, 0x1ac00000
	v_lshlrev_b32_e32 v14, 6, v12
	v_and_b32_e32 v15, 48, v10
	s_movk_i32 s6, 0x3c0
	s_mov_b64 s[74:75], 0x80
	s_addc_u32 s73, s15, 0
	v_ashrrev_i32_e32 v13, 6, v10
	v_and_or_b32 v14, v14, s6, v15
	v_readlane_b32 s6, v237, 9
	s_add_i32 m0, s3, 0x18000
	v_lshl_add_u64 v[8:9], v[8:9], 0, s[74:75]
	v_lshl_add_u32 v16, v13, 10, s6
	v_readlane_b32 s6, v237, 22
	s_waitcnt vmcnt(2)
	s_barrier
	global_load_lds_dwordx4 v[8:9], off
	v_lshl_add_u64 v[6:7], v[6:7], 0, s[74:75]
	s_add_i32 m0, s3, 0x1a000
	s_add_i32 s36, s3, 0x8000
	s_add_i32 s37, s3, 0xa000
	v_add_lshl_u32 v13, v13, s6, 10
	global_load_lds_dwordx4 v[6:7], off
	v_lshl_add_u64 v[2:3], v[2:3], 0, s[74:75]
	s_mov_b32 m0, s36
	s_add_u32 s6, s58, 0x10080
	global_load_lds_dwordx4 v[2:3], off
	v_lshl_add_u64 v[2:3], v[4:5], 0, s[74:75]
	s_mov_b32 m0, s37
	s_addc_u32 s7, s59, 0
	global_load_lds_dwordx4 v[2:3], off
	s_add_i32 m0, s3, 0x1c000
	v_lshl_add_u64 v[2:3], s[6:7], 0, v[146:147]
	global_load_lds_dwordx4 v[2:3], off
	v_lshl_add_u64 v[2:3], s[6:7], 0, v[148:149]
	s_add_i32 m0, s3, 0x1e000
	v_lshlrev_b32_e32 v12, 2, v12
	global_load_lds_dwordx4 v[2:3], off
	s_cmpk_lt_u32 s76, 0x100
	v_and_b32_e32 v12, 32, v12
	v_lshlrev_b32_e32 v10, 2, v10
	s_waitcnt vmcnt(6)
	s_cselect_b64 s[76:77], -1, 0
	s_ashr_i32 s47, s81, 31
	v_bitop3_b32 v12, v14, v16, v12 bitop3:0xde
	v_lshl_or_b32 v11, v11, 6, v15
	v_and_b32_e32 v10, 32, v10
	s_cmp_eq_u64 s[16:17], 0
	v_bitop3_b32 v165, v11, v13, v10 bitop3:0xde
	s_mov_b32 s34, 0x8000
	v_cmp_gt_u32_e64 s[6:7], 64, v0
	s_cselect_b64 s[78:79], -1, 0
	s_add_i32 s49, 0, 0x10000
	s_add_i32 s40, 0, 0x14000
	v_add_u32_e32 v166, 0, v12
	s_movk_i32 s41, 0x600
	s_mov_b32 s80, 0x3e16c740
	v_mov_b64_e32 v[152:153], 0x4b4
	v_mov_b64_e32 v[154:155], 0x4b3
	v_mov_b64_e32 v[156:157], 0x1e8481
	v_mov_b32_e32 v167, 0x800
	v_mov_b32_e32 v168, 0x3e16c740
	v_mov_b32_e32 v2, v151
	v_mov_b32_e32 v3, v151
	v_mov_b32_e32 v4, v151
	v_mov_b32_e32 v5, v151
	v_mov_b32_e32 v6, v151
	v_mov_b32_e32 v7, v151
	v_mov_b32_e32 v8, v151
	v_mov_b32_e32 v9, v151
	v_mov_b32_e32 v10, v151
	v_mov_b32_e32 v11, v151
	v_mov_b32_e32 v12, v151
	v_mov_b32_e32 v13, v151
	v_mov_b32_e32 v14, v151
	v_mov_b32_e32 v15, v151
	v_mov_b32_e32 v16, v151
	v_mov_b32_e32 v17, v151
	v_mov_b32_e32 v18, v151
	v_mov_b32_e32 v19, v151
	v_mov_b32_e32 v20, v151
	v_mov_b32_e32 v21, v151
	v_mov_b32_e32 v22, v151
	v_mov_b32_e32 v23, v151
	v_mov_b32_e32 v24, v151
	v_mov_b32_e32 v25, v151
	v_mov_b32_e32 v26, v151
	v_mov_b32_e32 v27, v151
	v_mov_b32_e32 v28, v151
	v_mov_b32_e32 v29, v151
	v_mov_b32_e32 v30, v151
	v_mov_b32_e32 v31, v151
	v_mov_b32_e32 v32, v151
	v_mov_b32_e32 v33, v151
	v_mov_b32_e32 v34, v151
	v_mov_b32_e32 v35, v151
	v_mov_b32_e32 v36, v151
	v_mov_b32_e32 v37, v151
	v_mov_b32_e32 v38, v151
	v_mov_b32_e32 v39, v151
	v_mov_b32_e32 v40, v151
	v_mov_b32_e32 v41, v151
	v_mov_b32_e32 v42, v151
	v_mov_b32_e32 v43, v151
	v_mov_b32_e32 v44, v151
	v_mov_b32_e32 v45, v151
	v_mov_b32_e32 v46, v151
	v_mov_b32_e32 v47, v151
	v_mov_b32_e32 v48, v151
	v_mov_b32_e32 v49, v151
	v_mov_b32_e32 v50, v151
	v_mov_b32_e32 v51, v151
	v_mov_b32_e32 v52, v151
	v_mov_b32_e32 v53, v151
	v_mov_b32_e32 v54, v151
	v_mov_b32_e32 v55, v151
	v_mov_b32_e32 v56, v151
	v_mov_b32_e32 v57, v151
	v_mov_b32_e32 v58, v151
	v_mov_b32_e32 v59, v151
	v_mov_b32_e32 v60, v151
	v_mov_b32_e32 v61, v151
	v_mov_b32_e32 v62, v151
	v_mov_b32_e32 v63, v151
	v_mov_b32_e32 v64, v151
	v_mov_b32_e32 v65, v151
	v_mov_b32_e32 v66, v151
	v_mov_b32_e32 v67, v151
	v_mov_b32_e32 v68, v151
	v_mov_b32_e32 v69, v151
	v_mov_b32_e32 v70, v151
	v_mov_b32_e32 v71, v151
	v_mov_b32_e32 v72, v151
	v_mov_b32_e32 v73, v151
	v_mov_b32_e32 v74, v151
	v_mov_b32_e32 v75, v151
	v_mov_b32_e32 v76, v151
	v_mov_b32_e32 v77, v151
	v_mov_b32_e32 v78, v151
	v_mov_b32_e32 v79, v151
	v_mov_b32_e32 v80, v151
	v_mov_b32_e32 v81, v151
	v_mov_b32_e32 v82, v151
	v_mov_b32_e32 v83, v151
	v_mov_b32_e32 v84, v151
	v_mov_b32_e32 v85, v151
	v_mov_b32_e32 v86, v151
	v_mov_b32_e32 v87, v151
	v_mov_b32_e32 v88, v151
	v_mov_b32_e32 v89, v151
	v_mov_b32_e32 v90, v151
	v_mov_b32_e32 v91, v151
	v_mov_b32_e32 v92, v151
	v_mov_b32_e32 v93, v151
	v_mov_b32_e32 v94, v151
	v_mov_b32_e32 v95, v151
	v_mov_b32_e32 v96, v151
	v_mov_b32_e32 v97, v151
	v_mov_b32_e32 v98, v151
	v_mov_b32_e32 v99, v151
	v_mov_b32_e32 v100, v151
	v_mov_b32_e32 v101, v151
	v_mov_b32_e32 v102, v151
	v_mov_b32_e32 v103, v151
	v_mov_b32_e32 v104, v151
	v_mov_b32_e32 v105, v151
	v_mov_b32_e32 v106, v151
	v_mov_b32_e32 v107, v151
	v_mov_b32_e32 v108, v151
	v_mov_b32_e32 v109, v151
	v_mov_b32_e32 v110, v151
	v_mov_b32_e32 v111, v151
	v_mov_b32_e32 v112, v151
	v_mov_b32_e32 v113, v151
	v_mov_b32_e32 v114, v151
	v_mov_b32_e32 v115, v151
	v_mov_b32_e32 v116, v151
	v_mov_b32_e32 v117, v151
	v_mov_b32_e32 v118, v151
	v_mov_b32_e32 v119, v151
	v_mov_b32_e32 v120, v151
	v_mov_b32_e32 v121, v151
	v_mov_b32_e32 v122, v151
	v_mov_b32_e32 v123, v151
	v_mov_b32_e32 v124, v151
	v_mov_b32_e32 v125, v151
	v_mov_b32_e32 v126, v151
	v_mov_b32_e32 v127, v151
	v_mov_b32_e32 v128, v151
	v_mov_b32_e32 v129, v151
	s_barrier
	s_branch .LBB0_852

;     __device__ __forceinline__ const char* a_ptr(const Gemm& g, const Unit& u, size_t tsA) const { return (const char*)g.A + (size_t)u.pm * tsA + (size_t)u.pn * g.a_pn_bytes + (u.ks > 0 ? (size_t)u.ks * g.ks_bytes : 0); }
;     __device__ __forceinline__ const char* b_ptr(const Gemm& g, const Unit& u, size_t tsB) const { return (const char*)g.Bt + (size_t)u.pn * tsB + (u.ks > 0 ? (size_t)u.ks * g.ks_bytes : 0); }
;     __device__ __forceinline__ const char* a_ptr(const Gemm& g, const Unit& u, size_t tsA) const { return (const char*)g.A + (size_t)u.pm * tsA + (size_t)u.pn * g.a_pn_bytes + (u.ks > 0 ? (size_t)u.ks * g.ks_bytes : 0); }
;     __device__ __forceinline__ const char* b_ptr(const Gemm& g, const Unit& u, size_t tsB) const { return (const char*)g.Bt + (size_t)u.pn * tsB + (u.ks > 0 ? (size_t)u.ks * g.ks_bytes : 0); }
; template <class Epi, class Sched, bool ALIGN_EPI = false, bool SP2 = false>
; __device__ __forceinline__ void gemm_phase(PG8_LAS unsigned char* lds, const Gemm g, const Sched& S, const Epi& E, const int wid) {
;     ...
;     for (;;) {
;         const bool has_next = S.next(ui + 1, nxt);
;         const char* nA = has_next ? S.a_ptr(g, nxt, tsA) : cA; const char* nB = has_next ? S.b_ptr(g, nxt, tsB) : cB;
;         const int nt = cur.ks >= 0 ? g.nt_split : ntfull;
.LBB0_852:
	s_add_i32 s27, s42, 1
	s_mul_i32 s8, s27, s33
	s_mul_hi_i32 s9, s27, s33
	s_add_u32 s8, s8, s81
	s_addc_u32 s9, s9, s47
	s_cmpk_gt_i32 s8, 0x1ff
	s_mov_b32 s43, 0
	s_cselect_b64 s[10:11], -1, 0
	s_cmpk_lt_i32 s8, 0x200
	s_mov_b32 s24, s8
	s_mov_b64 s[90:91], 0
	s_cbranch_scc1 .LBB0_860
	s_cmpk_lt_u32 s8, 0x494
	s_cselect_b32 s12, 2, 3
	s_cmpk_gt_u32 s8, 0x38b
	s_cselect_b32 s14, s12, 1
	s_cmp_lt_i32 s14, 2
	s_mov_b64 s[12:13], -1
	s_cbranch_scc1 .LBB0_858
	s_cmp_lg_u32 s14, 2
	s_mov_b64 s[14:15], -1
	s_cbranch_scc0 .LBB0_856
	s_add_i32 s24, s8, 0xfffffb6c
	s_mov_b64 s[14:15], 0

;     __device__ __forceinline__ void operator()(const f32x4 (&acc)[2][2][4][2], const Unit& u, int wr, int wc, int fr, int fq) const {
;     ...
;         int row0b = row0, col0b = col0; asm volatile("" : "+v"(row0b), "+v"(col0b));
;         f32x4 c1[2][2], c2[2][2];
; #pragma unroll
;         for (int bj = 0; bj < 2; ++bj)
; #pragma unroll
;             for (int n = 0; n < 2; ++n) { c1[bj][n] = *(const f32x4*)(g + col0b + bj * HALF + n * 16);
;                 if (MODE == 0) { const float* mr = mod + (size_t)((u.pm * BM) >> 11) * NMOD + col0b + bj * HALF + n * 16; c1[bj][n] = c1[bj][n] * (*(const f32x4*)(mr + 4096) + 1.f); c2[bj][n] = *(const f32x4*)(mr + 3072); } }
.LBB0_1325:
	s_or_b64 exec, exec, s[14:15]
	v_mov_b32_e32 v218, v200
	v_mov_b32_e32 v166, v198
	s_waitcnt lgkmcnt(0)
	s_barrier
	s_add_u32 s12, s96, s71
	s_addc_u32 s13, s97, s69
	v_lshlrev_b64 v[182:183], 2, v[200:201]
	v_lshl_add_u64 v[184:185], s[12:13], 0, v[182:183]
	s_mov_b64 s[14:15], 0x4000
	s_mov_b64 s[76:77], 0x3000
	v_lshl_add_u64 v[162:163], v[184:185], 0, s[14:15]
	v_lshl_add_u64 v[164:165], s[40:41], 0, v[182:183]
	v_lshl_add_u64 v[184:185], v[184:185], 0, s[76:77]
	global_load_dwordx4 v[130:133], v[162:163], off
	global_load_dwordx4 v[146:149], v[164:165], off
	global_load_dwordx4 v[166:169], v[184:185], off
	global_load_dwordx4 v[134:137], v[162:163], off offset:64
	global_load_dwordx4 v[150:153], v[164:165], off offset:64
	global_load_dwordx4 v[170:173], v[184:185], off offset:64
	global_load_dwordx4 v[138:141], v[162:163], off offset:512
	global_load_dwordx4 v[154:157], v[164:165], off offset:512
	global_load_dwordx4 v[174:177], v[184:185], off offset:512
	global_load_dwordx4 v[142:145], v[162:163], off offset:576
	global_load_dwordx4 v[158:161], v[164:165], off offset:576
	global_load_dwordx4 v[178:181], v[184:185], off offset:576
	v_lshl_add_u32 v199, v223, 2, s84
	ds_read_b32 v202, v199 offset:4096
	ds_read_b32 v204, v199 offset:4160
	ds_read_b32 v206, v199 offset:4224
	ds_read_b32 v208, v199 offset:4288
	ds_read_b32 v210, v199 offset:4608
	ds_read_b32 v212, v199 offset:4672
	ds_read_b32 v214, v199 offset:4736
	ds_read_b32 v216, v199 offset:4800
	v_add_u32_e32 v222, s47, v223
	v_ashrrev_i32_e32 v223, 31, v222
	v_lshlrev_b64 v[226:227], 11, v[222:223]
	v_lshlrev_b64 v[182:183], 1, v[200:201]
	v_lshl_add_u64 v[246:247], s[48:49], 0, v[226:227]
	v_lshl_add_u64 v[226:227], s[50:51], 0, v[226:227]
	v_lshl_add_u64 v[246:247], v[246:247], 0, v[182:183]
	v_lshl_add_u64 v[226:227], v[226:227], 0, v[182:183]
	s_mov_b64 s[14:15], 0x8000
	s_mov_b64 s[76:77], 0x28000
	v_and_b32_e32 v184, 16, v225
	v_lshrrev_b32_e32 v184, 4, v184
	v_mul_u32_u24_e32 v184, 24, v184
	v_mov_b32_e32 v185, 0
	v_lshl_add_u64 v[246:247], v[246:247], 0, v[184:185]
	v_lshl_add_u64 v[226:227], v[226:227], 0, v[184:185]
	v_cvt_pk_bf16_f32 v218, v126, v127
	v_cvt_pk_bf16_f32 v219, v128, v129
	v_cvt_pk_bf16_f32 v220, v122, v123
	v_cvt_pk_bf16_f32 v221, v124, v125
	s_nop 1
	v_permlane16_swap_b32_e32 v218, v220
	v_permlane16_swap_b32_e32 v219, v221
	global_store_dwordx4 v[246:247], v[218:221], off
	v_cvt_pk_bf16_f32 v238, v110, v111
	v_cvt_pk_bf16_f32 v239, v112, v113
	v_cvt_pk_bf16_f32 v240, v102, v103
	v_cvt_pk_bf16_f32 v241, v104, v105
	s_nop 1
	v_permlane16_swap_b32_e32 v238, v240
	v_permlane16_swap_b32_e32 v239, v241
	global_store_dwordx4 v[246:247], v[238:241], off offset:256
	v_lshl_add_u64 v[246:247], v[246:247], 0, s[14:15]
	v_cvt_pk_bf16_f32 v242, v118, v119
	v_cvt_pk_bf16_f32 v243, v120, v121
	v_cvt_pk_bf16_f32 v244, v114, v115
	v_cvt_pk_bf16_f32 v245, v116, v117
	s_nop 1
	v_permlane16_swap_b32_e32 v242, v244
	v_permlane16_swap_b32_e32 v243, v245
	global_store_dwordx4 v[246:247], v[242:245], off
	v_cvt_pk_bf16_f32 v162, v94, v95
	v_cvt_pk_bf16_f32 v163, v96, v97
	v_cvt_pk_bf16_f32 v164, v86, v87
	v_cvt_pk_bf16_f32 v165, v88, v89
	s_nop 1
	v_permlane16_swap_b32_e32 v162, v164
	v_permlane16_swap_b32_e32 v163, v165
	global_store_dwordx4 v[246:247], v[162:165], off offset:256
	v_lshl_add_u64 v[246:247], v[246:247], 0, s[14:15]
	v_cvt_pk_bf16_f32 v218, v106, v107
	v_cvt_pk_bf16_f32 v219, v108, v109
	v_cvt_pk_bf16_f32 v220, v98, v99
	v_cvt_pk_bf16_f32 v221, v100, v101
	s_nop 1
	v_permlane16_swap_b32_e32 v218, v220
	v_permlane16_swap_b32_e32 v219, v221
	global_store_dwordx4 v[246:247], v[218:221], off
	v_cvt_pk_bf16_f32 v238, v78, v79
	v_cvt_pk_bf16_f32 v239, v80, v81
	v_cvt_pk_bf16_f32 v240, v74, v75
	v_cvt_pk_bf16_f32 v241, v76, v77
	s_nop 1
	v_permlane16_swap_b32_e32 v238, v240
	v_permlane16_swap_b32_e32 v239, v241
	global_store_dwordx4 v[246:247], v[238:241], off offset:256
	v_lshl_add_u64 v[246:247], v[246:247], 0, s[14:15]
	v_cvt_pk_bf16_f32 v242, v90, v91
	v_cvt_pk_bf16_f32 v243, v92, v93
	v_cvt_pk_bf16_f32 v244, v82, v83
	v_cvt_pk_bf16_f32 v245, v84, v85
	s_nop 1
	v_permlane16_swap_b32_e32 v242, v244
	v_permlane16_swap_b32_e32 v243, v245
	global_store_dwordx4 v[246:247], v[242:245], off
	v_cvt_pk_bf16_f32 v162, v70, v71
	v_cvt_pk_bf16_f32 v163, v72, v73
	v_cvt_pk_bf16_f32 v164, v66, v67
	v_cvt_pk_bf16_f32 v165, v68, v69
	s_nop 1
	v_permlane16_swap_b32_e32 v162, v164
	v_permlane16_swap_b32_e32 v163, v165
	global_store_dwordx4 v[246:247], v[162:165], off offset:256
	v_lshl_add_u64 v[246:247], v[246:247], 0, s[76:77]
	v_cvt_pk_bf16_f32 v218, v62, v63
	v_cvt_pk_bf16_f32 v219, v64, v65
	v_cvt_pk_bf16_f32 v220, v58, v59
	v_cvt_pk_bf16_f32 v221, v60, v61
	s_nop 1
	v_permlane16_swap_b32_e32 v218, v220
	v_permlane16_swap_b32_e32 v219, v221
	global_store_dwordx4 v[246:247], v[218:221], off
	v_cvt_pk_bf16_f32 v238, v46, v47
	v_cvt_pk_bf16_f32 v239, v48, v49
	v_cvt_pk_bf16_f32 v240, v38, v39
	v_cvt_pk_bf16_f32 v241, v40, v41
	s_nop 1
	v_permlane16_swap_b32_e32 v238, v240
	v_permlane16_swap_b32_e32 v239, v241
	global_store_dwordx4 v[246:247], v[238:241], off offset:256
	v_lshl_add_u64 v[246:247], v[246:247], 0, s[14:15]
	v_cvt_pk_bf16_f32 v242, v54, v55
	v_cvt_pk_bf16_f32 v243, v56, v57
	v_cvt_pk_bf16_f32 v244, v50, v51
	v_cvt_pk_bf16_f32 v245, v52, v53
	s_nop 1
	v_permlane16_swap_b32_e32 v242, v244
	v_permlane16_swap_b32_e32 v243, v245
	global_store_dwordx4 v[246:247], v[242:245], off
	v_cvt_pk_bf16_f32 v162, v30, v31
	v_cvt_pk_bf16_f32 v163, v32, v33
	v_cvt_pk_bf16_f32 v164, v22, v23
	v_cvt_pk_bf16_f32 v165, v24, v25
	s_nop 1
	v_permlane16_swap_b32_e32 v162, v164
	v_permlane16_swap_b32_e32 v163, v165
	global_store_dwordx4 v[246:247], v[162:165], off offset:256
	v_lshl_add_u64 v[246:247], v[246:247], 0, s[14:15]
	v_cvt_pk_bf16_f32 v218, v42, v43
	v_cvt_pk_bf16_f32 v219, v44, v45
	v_cvt_pk_bf16_f32 v220, v34, v35
	v_cvt_pk_bf16_f32 v221, v36, v37
	s_nop 1
	v_permlane16_swap_b32_e32 v218, v220
	v_permlane16_swap_b32_e32 v219, v221
	global_store_dwordx4 v[246:247], v[218:221], off
	v_cvt_pk_bf16_f32 v238, v14, v15
	v_cvt_pk_bf16_f32 v239, v16, v17
	v_cvt_pk_bf16_f32 v240, v10, v11
	v_cvt_pk_bf16_f32 v241, v12, v13
	s_nop 1
	v_permlane16_swap_b32_e32 v238, v240
	v_permlane16_swap_b32_e32 v239, v241
	global_store_dwordx4 v[246:247], v[238:241], off offset:256
	v_lshl_add_u64 v[246:247], v[246:247], 0, s[14:15]
	v_cvt_pk_bf16_f32 v242, v26, v27
	v_cvt_pk_bf16_f32 v243, v28, v29
	v_cvt_pk_bf16_f32 v244, v18, v19
	v_cvt_pk_bf16_f32 v245, v20, v21
	s_nop 1
	v_permlane16_swap_b32_e32 v242, v244
	v_permlane16_swap_b32_e32 v243, v245
	global_store_dwordx4 v[246:247], v[242:245], off
	v_cvt_pk_bf16_f32 v162, v6, v7
	v_cvt_pk_bf16_f32 v163, v8, v9
	v_cvt_pk_bf16_f32 v164, v2, v3
	v_cvt_pk_bf16_f32 v165, v4, v5
	s_nop 1
	v_permlane16_swap_b32_e32 v162, v164
	v_permlane16_swap_b32_e32 v163, v165
	global_store_dwordx4 v[246:247], v[162:165], off offset:256
	s_waitcnt vmcnt(16) lgkmcnt(0)
;     __device__ __forceinline__ void operator()(const f32x4 (&acc)[2][2][4][2], const Unit& u, int wr, int wc, int fr, int fq) const {
;     ...
;             for (int n = 0; n < 2; ++n) { c1[bj][n] = *(const f32x4*)(g + col0b + bj * HALF + n * 16);
;                 if (MODE == 0) { const float* mr = mod + (size_t)((u.pm * BM) >> 11) * NMOD + col0b + bj * HALF + n * 16; c1[bj][n] = c1[bj][n] * (*(const f32x4*)(mr + 4096) + 1.f); c2[bj][n] = *(const f32x4*)(mr + 3072); } }
	v_pk_add_f32 v[130:131], v[130:131], 1.0 op_sel_hi:[1,0]
	v_pk_add_f32 v[132:133], v[132:133], 1.0 op_sel_hi:[1,0]
	v_pk_add_f32 v[134:135], v[134:135], 1.0 op_sel_hi:[1,0]
	v_pk_add_f32 v[136:137], v[136:137], 1.0 op_sel_hi:[1,0]
	v_pk_add_f32 v[138:139], v[138:139], 1.0 op_sel_hi:[1,0]
	v_pk_add_f32 v[140:141], v[140:141], 1.0 op_sel_hi:[1,0]
	v_pk_add_f32 v[142:143], v[142:143], 1.0 op_sel_hi:[1,0]
	v_pk_add_f32 v[144:145], v[144:145], 1.0 op_sel_hi:[1,0]
	v_pk_mul_f32 v[146:147], v[146:147], v[130:131]
	v_pk_mul_f32 v[148:149], v[148:149], v[132:133]
	v_pk_mul_f32 v[150:151], v[150:151], v[134:135]
	v_pk_mul_f32 v[152:153], v[152:153], v[136:137]
	v_pk_mul_f32 v[154:155], v[154:155], v[138:139]
	v_pk_mul_f32 v[156:157], v[156:157], v[140:141]
	v_pk_mul_f32 v[158:159], v[158:159], v[142:143]
	v_pk_mul_f32 v[160:161], v[160:161], v[144:145]
	v_pk_mul_f32 v[130:131], v[202:203], v[126:127] op_sel_hi:[0,1]
	v_pk_mul_f32 v[132:133], v[202:203], v[128:129] op_sel_hi:[0,1]
	v_pk_fma_f32 v[130:131], v[146:147], v[130:131], v[166:167]
	v_pk_fma_f32 v[132:133], v[148:149], v[132:133], v[168:169]
	v_pk_mul_f32 v[134:135], v[202:203], v[122:123] op_sel_hi:[0,1]
	v_pk_mul_f32 v[136:137], v[202:203], v[124:125] op_sel_hi:[0,1]
	v_pk_fma_f32 v[134:135], v[150:151], v[134:135], v[170:171]
	v_pk_fma_f32 v[136:137], v[152:153], v[136:137], v[172:173]
	v_cvt_pk_bf16_f32 v130, v130, v131
	v_cvt_pk_bf16_f32 v131, v132, v133
	v_cvt_pk_bf16_f32 v132, v134, v135
	v_cvt_pk_bf16_f32 v133, v136, v137
	s_nop 1
	v_permlane16_swap_b32_e32 v130, v132
	v_permlane16_swap_b32_e32 v131, v133
	global_store_dwordx4 v[226:227], v[130:133], off
	v_pk_mul_f32 v[138:139], v[202:203], v[110:111] op_sel_hi:[0,1]
	v_pk_mul_f32 v[140:141], v[202:203], v[112:113] op_sel_hi:[0,1]
	v_pk_fma_f32 v[138:139], v[154:155], v[138:139], v[174:175]
	v_pk_fma_f32 v[140:141], v[156:157], v[140:141], v[176:177]
	v_pk_mul_f32 v[142:143], v[202:203], v[102:103] op_sel_hi:[0,1]
	v_pk_mul_f32 v[144:145], v[202:203], v[104:105] op_sel_hi:[0,1]
	v_pk_fma_f32 v[142:143], v[158:159], v[142:143], v[178:179]
	v_pk_fma_f32 v[144:145], v[160:161], v[144:145], v[180:181]
	v_cvt_pk_bf16_f32 v138, v138, v139
	v_cvt_pk_bf16_f32 v139, v140, v141
	v_cvt_pk_bf16_f32 v140, v142, v143
	v_cvt_pk_bf16_f32 v141, v144, v145
	s_nop 1
	v_permlane16_swap_b32_e32 v138, v140
	v_permlane16_swap_b32_e32 v139, v141
	global_store_dwordx4 v[226:227], v[138:141], off offset:256
	v_lshl_add_u64 v[226:227], v[226:227], 0, s[14:15]
	v_pk_mul_f32 v[238:239], v[204:205], v[118:119] op_sel_hi:[0,1]
	v_pk_mul_f32 v[240:241], v[204:205], v[120:121] op_sel_hi:[0,1]
	v_pk_fma_f32 v[238:239], v[146:147], v[238:239], v[166:167]
	v_pk_fma_f32 v[240:241], v[148:149], v[240:241], v[168:169]
	v_pk_mul_f32 v[242:243], v[204:205], v[114:115] op_sel_hi:[0,1]
	v_pk_mul_f32 v[244:245], v[204:205], v[116:117] op_sel_hi:[0,1]
	v_pk_fma_f32 v[242:243], v[150:151], v[242:243], v[170:171]
	v_pk_fma_f32 v[244:245], v[152:153], v[244:245], v[172:173]
	v_cvt_pk_bf16_f32 v238, v238, v239
	v_cvt_pk_bf16_f32 v239, v240, v241
	v_cvt_pk_bf16_f32 v240, v242, v243
	v_cvt_pk_bf16_f32 v241, v244, v245
	s_nop 1
	v_permlane16_swap_b32_e32 v238, v240
	v_permlane16_swap_b32_e32 v239, v241
	global_store_dwordx4 v[226:227], v[238:241], off
	v_pk_mul_f32 v[130:131], v[204:205], v[94:95] op_sel_hi:[0,1]
	v_pk_mul_f32 v[132:133], v[204:205], v[96:97] op_sel_hi:[0,1]
	v_pk_fma_f32 v[130:131], v[154:155], v[130:131], v[174:175]
	v_pk_fma_f32 v[132:133], v[156:157], v[132:133], v[176:177]
	v_pk_mul_f32 v[134:135], v[204:205], v[86:87] op_sel_hi:[0,1]
	v_pk_mul_f32 v[136:137], v[204:205], v[88:89] op_sel_hi:[0,1]
	v_pk_fma_f32 v[134:135], v[158:159], v[134:135], v[178:179]
	v_pk_fma_f32 v[136:137], v[160:161], v[136:137], v[180:181]
	v_cvt_pk_bf16_f32 v130, v130, v131
	v_cvt_pk_bf16_f32 v131, v132, v133
	v_cvt_pk_bf16_f32 v132, v134, v135
	v_cvt_pk_bf16_f32 v133, v136, v137
	s_nop 1
	v_permlane16_swap_b32_e32 v130, v132
	v_permlane16_swap_b32_e32 v131, v133
	global_store_dwordx4 v[226:227], v[130:133], off offset:256
	v_lshl_add_u64 v[226:227], v[226:227], 0, s[14:15]
	v_pk_mul_f32 v[138:139], v[206:207], v[106:107] op_sel_hi:[0,1]
	v_pk_mul_f32 v[140:141], v[206:207], v[108:109] op_sel_hi:[0,1]
	v_pk_fma_f32 v[138:139], v[146:147], v[138:139], v[166:167]
	v_pk_fma_f32 v[140:141], v[148:149], v[140:141], v[168:169]
	v_pk_mul_f32 v[142:143], v[206:207], v[98:99] op_sel_hi:[0,1]
	v_pk_mul_f32 v[144:145], v[206:207], v[100:101] op_sel_hi:[0,1]
	v_pk_fma_f32 v[142:143], v[150:151], v[142:143], v[170:171]
	v_pk_fma_f32 v[144:145], v[152:153], v[144:145], v[172:173]
	v_cvt_pk_bf16_f32 v138, v138, v139
	v_cvt_pk_bf16_f32 v139, v140, v141
	v_cvt_pk_bf16_f32 v140, v142, v143
	v_cvt_pk_bf16_f32 v141, v144, v145
	s_nop 1
	v_permlane16_swap_b32_e32 v138, v140
	v_permlane16_swap_b32_e32 v139, v141
	global_store_dwordx4 v[226:227], v[138:141], off
	v_pk_mul_f32 v[238:239], v[206:207], v[78:79] op_sel_hi:[0,1]
	v_pk_mul_f32 v[240:241], v[206:207], v[80:81] op_sel_hi:[0,1]
	v_pk_fma_f32 v[238:239], v[154:155], v[238:239], v[174:175]
	v_pk_fma_f32 v[240:241], v[156:157], v[240:241], v[176:177]
	v_pk_mul_f32 v[242:243], v[206:207], v[74:75] op_sel_hi:[0,1]
	v_pk_mul_f32 v[244:245], v[206:207], v[76:77] op_sel_hi:[0,1]
	v_pk_fma_f32 v[242:243], v[158:159], v[242:243], v[178:179]
	v_pk_fma_f32 v[244:245], v[160:161], v[244:245], v[180:181]
	v_cvt_pk_bf16_f32 v238, v238, v239
	v_cvt_pk_bf16_f32 v239, v240, v241
	v_cvt_pk_bf16_f32 v240, v242, v243
	v_cvt_pk_bf16_f32 v241, v244, v245
	s_nop 1
	v_permlane16_swap_b32_e32 v238, v240
	v_permlane16_swap_b32_e32 v239, v241
; #define EN_LOAD(BUF, G) do { const size_t bi_ = (size_t)(row0b + ((G) >> 2) * HALF + ((G) & 3) * 16) * DM + col0b; \
;             _Pragma("unroll") for (int bj = 0; bj < 2; ++bj) _Pragma("unroll") for (int n = 0; n < 2; ++n) BUF[bj][n] = ldb(baseP, bi_ + bj * HALF + n * 16); } while (0)
;     __device__ __forceinline__ void operator()(const f32x4 (&acc)[2][2][4][2], const Unit& u, int wr, int wc, int fr, int fq) const {
;     ...
;         f32x4 bA[2][2], bB[2][2];
;         EN_LOAD(bA, 0); EN_LOAD(bB, 1);
;         EN_DONE(bA, 0); EN_LOAD(bA, 2); EN_DONE(bB, 1); EN_LOAD(bB, 3);
;         EN_DONE(bA, 2); EN_LOAD(bA, 4); EN_DONE(bB, 3); EN_LOAD(bB, 5);
;         EN_DONE(bA, 4); EN_LOAD(bA, 6); EN_DONE(bB, 5); EN_LOAD(bB, 7);
;         EN_DONE(bA, 6); EN_DONE(bB, 7);
	global_store_dwordx4 v[226:227], v[238:241], off offset:256
	v_lshl_add_u64 v[226:227], v[226:227], 0, s[14:15]
	v_pk_mul_f32 v[130:131], v[208:209], v[90:91] op_sel_hi:[0,1]
	v_pk_mul_f32 v[132:133], v[208:209], v[92:93] op_sel_hi:[0,1]
	v_pk_fma_f32 v[130:131], v[146:147], v[130:131], v[166:167]
	v_pk_fma_f32 v[132:133], v[148:149], v[132:133], v[168:169]
	v_pk_mul_f32 v[134:135], v[208:209], v[82:83] op_sel_hi:[0,1]
	v_pk_mul_f32 v[136:137], v[208:209], v[84:85] op_sel_hi:[0,1]
	v_pk_fma_f32 v[134:135], v[150:151], v[134:135], v[170:171]
	v_pk_fma_f32 v[136:137], v[152:153], v[136:137], v[172:173]
	v_cvt_pk_bf16_f32 v130, v130, v131
	v_cvt_pk_bf16_f32 v131, v132, v133
	v_cvt_pk_bf16_f32 v132, v134, v135
	v_cvt_pk_bf16_f32 v133, v136, v137
	s_nop 1
	v_permlane16_swap_b32_e32 v130, v132
	v_permlane16_swap_b32_e32 v131, v133
	global_store_dwordx4 v[226:227], v[130:133], off
	v_pk_mul_f32 v[138:139], v[208:209], v[70:71] op_sel_hi:[0,1]
	v_pk_mul_f32 v[140:141], v[208:209], v[72:73] op_sel_hi:[0,1]
	v_pk_fma_f32 v[138:139], v[154:155], v[138:139], v[174:175]
	v_pk_fma_f32 v[140:141], v[156:157], v[140:141], v[176:177]
	v_pk_mul_f32 v[142:143], v[208:209], v[66:67] op_sel_hi:[0,1]
	v_pk_mul_f32 v[144:145], v[208:209], v[68:69] op_sel_hi:[0,1]
	v_pk_fma_f32 v[142:143], v[158:159], v[142:143], v[178:179]
	v_pk_fma_f32 v[144:145], v[160:161], v[144:145], v[180:181]
	v_cvt_pk_bf16_f32 v138, v138, v139
	v_cvt_pk_bf16_f32 v139, v140, v141
	v_cvt_pk_bf16_f32 v140, v142, v143
	v_cvt_pk_bf16_f32 v141, v144, v145
	s_nop 1
	v_permlane16_swap_b32_e32 v138, v140
	v_permlane16_swap_b32_e32 v139, v141
	global_store_dwordx4 v[226:227], v[138:141], off offset:256
	v_lshl_add_u64 v[226:227], v[226:227], 0, s[76:77]
	v_pk_mul_f32 v[238:239], v[210:211], v[62:63] op_sel_hi:[0,1]
	v_pk_mul_f32 v[240:241], v[210:211], v[64:65] op_sel_hi:[0,1]
	v_pk_fma_f32 v[238:239], v[146:147], v[238:239], v[166:167]
	v_pk_fma_f32 v[240:241], v[148:149], v[240:241], v[168:169]
	v_pk_mul_f32 v[242:243], v[210:211], v[58:59] op_sel_hi:[0,1]
	v_pk_mul_f32 v[244:245], v[210:211], v[60:61] op_sel_hi:[0,1]
	v_pk_fma_f32 v[242:243], v[150:151], v[242:243], v[170:171]
	v_pk_fma_f32 v[244:245], v[152:153], v[244:245], v[172:173]
	v_cvt_pk_bf16_f32 v238, v238, v239
	v_cvt_pk_bf16_f32 v239, v240, v241
	v_cvt_pk_bf16_f32 v240, v242, v243
	v_cvt_pk_bf16_f32 v241, v244, v245
	s_nop 1
	v_permlane16_swap_b32_e32 v238, v240
	v_permlane16_swap_b32_e32 v239, v241
	global_store_dwordx4 v[226:227], v[238:241], off
	v_pk_mul_f32 v[130:131], v[210:211], v[46:47] op_sel_hi:[0,1]
	v_pk_mul_f32 v[132:133], v[210:211], v[48:49] op_sel_hi:[0,1]
	v_pk_fma_f32 v[130:131], v[154:155], v[130:131], v[174:175]
	v_pk_fma_f32 v[132:133], v[156:157], v[132:133], v[176:177]
	v_pk_mul_f32 v[134:135], v[210:211], v[38:39] op_sel_hi:[0,1]
	v_pk_mul_f32 v[136:137], v[210:211], v[40:41] op_sel_hi:[0,1]
	v_pk_fma_f32 v[134:135], v[158:159], v[134:135], v[178:179]
	v_pk_fma_f32 v[136:137], v[160:161], v[136:137], v[180:181]
	v_cvt_pk_bf16_f32 v130, v130, v131
	v_cvt_pk_bf16_f32 v131, v132, v133
	v_cvt_pk_bf16_f32 v132, v134, v135
	v_cvt_pk_bf16_f32 v133, v136, v137
	s_nop 1
	v_permlane16_swap_b32_e32 v130, v132
	v_permlane16_swap_b32_e32 v131, v133
	global_store_dwordx4 v[226:227], v[130:133], off offset:256
	v_lshl_add_u64 v[226:227], v[226:227], 0, s[14:15]
	v_pk_mul_f32 v[138:139], v[212:213], v[54:55] op_sel_hi:[0,1]
	v_pk_mul_f32 v[140:141], v[212:213], v[56:57] op_sel_hi:[0,1]
	v_pk_fma_f32 v[138:139], v[146:147], v[138:139], v[166:167]
	v_pk_fma_f32 v[140:141], v[148:149], v[140:141], v[168:169]
	v_pk_mul_f32 v[142:143], v[212:213], v[50:51] op_sel_hi:[0,1]
	v_pk_mul_f32 v[144:145], v[212:213], v[52:53] op_sel_hi:[0,1]
	v_pk_fma_f32 v[142:143], v[150:151], v[142:143], v[170:171]
	v_pk_fma_f32 v[144:145], v[152:153], v[144:145], v[172:173]
	v_cvt_pk_bf16_f32 v138, v138, v139
	v_cvt_pk_bf16_f32 v139, v140, v141
	v_cvt_pk_bf16_f32 v140, v142, v143
	v_cvt_pk_bf16_f32 v141, v144, v145
	s_nop 1
	v_permlane16_swap_b32_e32 v138, v140
	v_permlane16_swap_b32_e32 v139, v141
; #define EN_LOAD(BUF, G) do { const size_t bi_ = (size_t)(row0b + ((G) >> 2) * HALF + ((G) & 3) * 16) * DM + col0b; \
;             _Pragma("unroll") for (int bj = 0; bj < 2; ++bj) _Pragma("unroll") for (int n = 0; n < 2; ++n) BUF[bj][n] = ldb(baseP, bi_ + bj * HALF + n * 16); } while (0)
;     __device__ __forceinline__ void operator()(const f32x4 (&acc)[2][2][4][2], const Unit& u, int wr, int wc, int fr, int fq) const {
;     ...
;         f32x4 bA[2][2], bB[2][2];
;         EN_LOAD(bA, 0); EN_LOAD(bB, 1);
;         EN_DONE(bA, 0); EN_LOAD(bA, 2); EN_DONE(bB, 1); EN_LOAD(bB, 3);
;         EN_DONE(bA, 2); EN_LOAD(bA, 4); EN_DONE(bB, 3); EN_LOAD(bB, 5);
;         EN_DONE(bA, 4); EN_LOAD(bA, 6); EN_DONE(bB, 5); EN_LOAD(bB, 7);
;         EN_DONE(bA, 6); EN_DONE(bB, 7);
	global_store_dwordx4 v[226:227], v[138:141], off
	v_pk_mul_f32 v[238:239], v[212:213], v[30:31] op_sel_hi:[0,1]
	v_pk_mul_f32 v[240:241], v[212:213], v[32:33] op_sel_hi:[0,1]
	v_pk_fma_f32 v[238:239], v[154:155], v[238:239], v[174:175]
	v_pk_fma_f32 v[240:241], v[156:157], v[240:241], v[176:177]
	v_pk_mul_f32 v[242:243], v[212:213], v[22:23] op_sel_hi:[0,1]
	v_pk_mul_f32 v[244:245], v[212:213], v[24:25] op_sel_hi:[0,1]
	v_pk_fma_f32 v[242:243], v[158:159], v[242:243], v[178:179]
	v_pk_fma_f32 v[244:245], v[160:161], v[244:245], v[180:181]
	v_cvt_pk_bf16_f32 v238, v238, v239
	v_cvt_pk_bf16_f32 v239, v240, v241
	v_cvt_pk_bf16_f32 v240, v242, v243
	v_cvt_pk_bf16_f32 v241, v244, v245
	s_nop 1
	v_permlane16_swap_b32_e32 v238, v240
	v_permlane16_swap_b32_e32 v239, v241
	global_store_dwordx4 v[226:227], v[238:241], off offset:256
	v_lshl_add_u64 v[226:227], v[226:227], 0, s[14:15]
	v_pk_mul_f32 v[130:131], v[214:215], v[42:43] op_sel_hi:[0,1]
	v_pk_mul_f32 v[132:133], v[214:215], v[44:45] op_sel_hi:[0,1]
	v_pk_fma_f32 v[130:131], v[146:147], v[130:131], v[166:167]
	v_pk_fma_f32 v[132:133], v[148:149], v[132:133], v[168:169]
	v_pk_mul_f32 v[134:135], v[214:215], v[34:35] op_sel_hi:[0,1]
	v_pk_mul_f32 v[136:137], v[214:215], v[36:37] op_sel_hi:[0,1]
	v_pk_fma_f32 v[134:135], v[150:151], v[134:135], v[170:171]
	v_pk_fma_f32 v[136:137], v[152:153], v[136:137], v[172:173]
	v_cvt_pk_bf16_f32 v130, v130, v131
	v_cvt_pk_bf16_f32 v131, v132, v133
	v_cvt_pk_bf16_f32 v132, v134, v135
	v_cvt_pk_bf16_f32 v133, v136, v137
	s_nop 1
	v_permlane16_swap_b32_e32 v130, v132
	v_permlane16_swap_b32_e32 v131, v133
	global_store_dwordx4 v[226:227], v[130:133], off
	v_pk_mul_f32 v[138:139], v[214:215], v[14:15] op_sel_hi:[0,1]
	v_pk_mul_f32 v[140:141], v[214:215], v[16:17] op_sel_hi:[0,1]
	v_pk_fma_f32 v[138:139], v[154:155], v[138:139], v[174:175]
	v_pk_fma_f32 v[140:141], v[156:157], v[140:141], v[176:177]
	v_pk_mul_f32 v[142:143], v[214:215], v[10:11] op_sel_hi:[0,1]
	v_pk_mul_f32 v[144:145], v[214:215], v[12:13] op_sel_hi:[0,1]
	v_pk_fma_f32 v[142:143], v[158:159], v[142:143], v[178:179]
	v_pk_fma_f32 v[144:145], v[160:161], v[144:145], v[180:181]
	v_cvt_pk_bf16_f32 v138, v138, v139
	v_cvt_pk_bf16_f32 v139, v140, v141
	v_cvt_pk_bf16_f32 v140, v142, v143
	v_cvt_pk_bf16_f32 v141, v144, v145
	s_nop 1
	v_permlane16_swap_b32_e32 v138, v140
	v_permlane16_swap_b32_e32 v139, v141
	global_store_dwordx4 v[226:227], v[138:141], off offset:256
	v_lshl_add_u64 v[226:227], v[226:227], 0, s[14:15]
	v_pk_mul_f32 v[238:239], v[216:217], v[26:27] op_sel_hi:[0,1]
	v_pk_mul_f32 v[240:241], v[216:217], v[28:29] op_sel_hi:[0,1]
	v_pk_fma_f32 v[238:239], v[146:147], v[238:239], v[166:167]
	v_pk_fma_f32 v[240:241], v[148:149], v[240:241], v[168:169]
	v_pk_mul_f32 v[242:243], v[216:217], v[18:19] op_sel_hi:[0,1]
	v_pk_mul_f32 v[244:245], v[216:217], v[20:21] op_sel_hi:[0,1]
	v_pk_fma_f32 v[242:243], v[150:151], v[242:243], v[170:171]
	v_pk_fma_f32 v[244:245], v[152:153], v[244:245], v[172:173]
	v_cvt_pk_bf16_f32 v238, v238, v239
	v_cvt_pk_bf16_f32 v239, v240, v241
	v_cvt_pk_bf16_f32 v240, v242, v243
	v_cvt_pk_bf16_f32 v241, v244, v245
	s_nop 1
	v_permlane16_swap_b32_e32 v238, v240
	v_permlane16_swap_b32_e32 v239, v241
	global_store_dwordx4 v[226:227], v[238:241], off
	v_pk_mul_f32 v[130:131], v[216:217], v[6:7] op_sel_hi:[0,1]
	v_pk_mul_f32 v[132:133], v[216:217], v[8:9] op_sel_hi:[0,1]
	v_pk_fma_f32 v[130:131], v[154:155], v[130:131], v[174:175]
	v_pk_fma_f32 v[132:133], v[156:157], v[132:133], v[176:177]
	v_pk_mul_f32 v[134:135], v[216:217], v[2:3] op_sel_hi:[0,1]
	v_pk_mul_f32 v[136:137], v[216:217], v[4:5] op_sel_hi:[0,1]
	v_pk_fma_f32 v[134:135], v[158:159], v[134:135], v[178:179]
	v_pk_fma_f32 v[136:137], v[160:161], v[136:137], v[180:181]
	v_cvt_pk_bf16_f32 v130, v130, v131
	v_cvt_pk_bf16_f32 v131, v132, v133
	v_cvt_pk_bf16_f32 v132, v134, v135
	v_cvt_pk_bf16_f32 v133, v136, v137
	s_nop 1
	v_permlane16_swap_b32_e32 v130, v132
	v_permlane16_swap_b32_e32 v131, v133
	global_store_dwordx4 v[226:227], v[130:133], off offset:256
	s_mov_b64 s[12:13], 0
